# mods phase GEMV: all 64 weights of a thread requested up front (40 before the silu staging, 24 after), dot products from registers with packed FMAs
# baseline (speedup 1.0000x reference)
; __device__ __forceinline__ float siluf(float x) { return x * frcp(1.f + fexp(-x)); }
; __device__ void mods_phase(unsigned char* lds, const Params& p) {
;     ...
;   for (int tile = blockIdx.x; tile < 384; tile += gridDim.x) {
;     const int l = tile / 192, cb = (tile % 192) * 32;
;     for (int i = tid; i < 9 * 1024; i += 512) {
;       float v = (i < 8192) ? c[i] : cc[i - 8192];
;       sl[i] = siluf(v);
;     }
;     ...
;     const float* aw = p.in[4] + (size_t)l * 1024 * 6144 + cb + cl;
;     float acc[9];
; #pragma unroll
;     for (int r = 0; r < 9; ++r) acc[r] = 0.f;
;     for (int k0 = ks * 64; k0 < ks * 64 + 64; k0 += 16) {
;       float av[16];
; #pragma unroll
;       for (int u = 0; u < 16; ++u) av[u] = aw[(size_t)(k0 + u) * 6144];
.LBB0_8:
	s_and_saveexec_b64 s[16:17], vcc
	s_load_dwordx16 s[44:59], s[0:1], 0x0
	s_cbranch_execz .LBB0_11
	s_waitcnt lgkmcnt(0)
	s_cmpk_ge_i32 s40, 0xc0
	s_cselect_b32 s60, 0x1800000, 0
	s_cselect_b32 s61, 0xc0, 0
	s_sub_i32 s61, s40, s61
	s_lshl_b32 s61, s61, 7
	s_add_u32 s60, s60, s61
	s_add_u32 s60, s52, s60
	s_addc_u32 s61, s53, 0
	v_and_b32_e32 v66, 31, v134
	v_mul_u32_u24_e32 v67, 0x180000, v136
	v_lshl_add_u32 v66, v66, 2, v67
	global_load_dword v2, v66, s[60:61]
	v_add_u32_e32 v66, 0x6000, v66
	global_load_dword v3, v66, s[60:61]
	v_add_u32_e32 v66, 0x6000, v66
	global_load_dword v4, v66, s[60:61]
	v_add_u32_e32 v66, 0x6000, v66
	global_load_dword v5, v66, s[60:61]
	v_add_u32_e32 v66, 0x6000, v66
	global_load_dword v6, v66, s[60:61]
	v_add_u32_e32 v66, 0x6000, v66
	global_load_dword v7, v66, s[60:61]
	v_add_u32_e32 v66, 0x6000, v66
	global_load_dword v8, v66, s[60:61]
	v_add_u32_e32 v66, 0x6000, v66
	global_load_dword v9, v66, s[60:61]
	v_add_u32_e32 v66, 0x6000, v66
	global_load_dword v10, v66, s[60:61]
	v_add_u32_e32 v66, 0x6000, v66
	global_load_dword v11, v66, s[60:61]
	v_add_u32_e32 v66, 0x6000, v66
	global_load_dword v12, v66, s[60:61]
	v_add_u32_e32 v66, 0x6000, v66
	global_load_dword v13, v66, s[60:61]
	v_add_u32_e32 v66, 0x6000, v66
	global_load_dword v14, v66, s[60:61]
	v_add_u32_e32 v66, 0x6000, v66
	global_load_dword v15, v66, s[60:61]
	v_add_u32_e32 v66, 0x6000, v66
	global_load_dword v16, v66, s[60:61]
	v_add_u32_e32 v66, 0x6000, v66
	global_load_dword v17, v66, s[60:61]
	v_add_u32_e32 v66, 0x6000, v66
	global_load_dword v18, v66, s[60:61]
	v_add_u32_e32 v66, 0x6000, v66
	global_load_dword v19, v66, s[60:61]
	v_add_u32_e32 v66, 0x6000, v66
	global_load_dword v20, v66, s[60:61]
	v_add_u32_e32 v66, 0x6000, v66
	global_load_dword v21, v66, s[60:61]
	v_add_u32_e32 v66, 0x6000, v66
	global_load_dword v22, v66, s[60:61]
	v_add_u32_e32 v66, 0x6000, v66
	global_load_dword v23, v66, s[60:61]
	v_add_u32_e32 v66, 0x6000, v66
	global_load_dword v24, v66, s[60:61]
	v_add_u32_e32 v66, 0x6000, v66
	global_load_dword v25, v66, s[60:61]
	v_add_u32_e32 v66, 0x6000, v66
	global_load_dword v26, v66, s[60:61]
	v_add_u32_e32 v66, 0x6000, v66
	global_load_dword v27, v66, s[60:61]
	v_add_u32_e32 v66, 0x6000, v66
	global_load_dword v28, v66, s[60:61]
	v_add_u32_e32 v66, 0x6000, v66
	global_load_dword v29, v66, s[60:61]
	v_add_u32_e32 v66, 0x6000, v66
	global_load_dword v30, v66, s[60:61]
	v_add_u32_e32 v66, 0x6000, v66
	global_load_dword v31, v66, s[60:61]
	v_add_u32_e32 v66, 0x6000, v66
	global_load_dword v32, v66, s[60:61]
	v_add_u32_e32 v66, 0x6000, v66
	global_load_dword v33, v66, s[60:61]
	v_add_u32_e32 v66, 0x6000, v66
	global_load_dword v34, v66, s[60:61]
	v_add_u32_e32 v66, 0x6000, v66
	global_load_dword v35, v66, s[60:61]
	v_add_u32_e32 v66, 0x6000, v66
	global_load_dword v36, v66, s[60:61]
	v_add_u32_e32 v66, 0x6000, v66
	global_load_dword v37, v66, s[60:61]
	v_add_u32_e32 v66, 0x6000, v66
	global_load_dword v38, v66, s[60:61]
	v_add_u32_e32 v66, 0x6000, v66
	global_load_dword v39, v66, s[60:61]
	v_add_u32_e32 v66, 0x6000, v66
	global_load_dword v40, v66, s[60:61]
	v_add_u32_e32 v66, 0x6000, v66
	global_load_dword v41, v66, s[60:61]
	v_add_u32_e32 v66, 0x6000, v66
	v_lshlrev_b32_e32 v118, 2, v134
	global_load_dword v100, v118, s[46:47]
	v_add_u32_e32 v119, 0x800, v118
	global_load_dword v101, v119, s[46:47]
	v_add_u32_e32 v119, 0x800, v119
	global_load_dword v102, v119, s[46:47]
	v_add_u32_e32 v119, 0x800, v119
	global_load_dword v103, v119, s[46:47]
	v_add_u32_e32 v119, 0x800, v119
	global_load_dword v104, v119, s[46:47]
	v_add_u32_e32 v119, 0x800, v119
	global_load_dword v105, v119, s[46:47]
	v_add_u32_e32 v119, 0x800, v119
	global_load_dword v106, v119, s[46:47]
	v_add_u32_e32 v119, 0x800, v119
	global_load_dword v107, v119, s[46:47]
	v_add_u32_e32 v119, 0x800, v119
	global_load_dword v108, v119, s[46:47]
	v_add_u32_e32 v119, 0x800, v119
	global_load_dword v109, v119, s[46:47]
	v_add_u32_e32 v119, 0x800, v119
	global_load_dword v110, v119, s[46:47]
	v_add_u32_e32 v119, 0x800, v119
	global_load_dword v111, v119, s[46:47]
	v_add_u32_e32 v119, 0x800, v119
	global_load_dword v112, v119, s[46:47]
	v_add_u32_e32 v119, 0x800, v119
	global_load_dword v113, v119, s[46:47]
	v_add_u32_e32 v119, 0x800, v119
	global_load_dword v114, v119, s[46:47]
	v_add_u32_e32 v119, 0x800, v119
	global_load_dword v115, v119, s[46:47]
	global_load_dword v116, v118, s[50:51]
	global_load_dword v117, v118, s[50:51] offset:2048
	s_waitcnt vmcnt(12)
	v_mul_f32_e32 v120, 0xbfb8aa3b, v100
	v_mul_f32_e32 v121, 0xbfb8aa3b, v101
	v_mul_f32_e32 v122, 0xbfb8aa3b, v102
	v_mul_f32_e32 v123, 0xbfb8aa3b, v103
	v_mul_f32_e32 v124, 0xbfb8aa3b, v104
	v_mul_f32_e32 v125, 0xbfb8aa3b, v105
	v_exp_f32_e32 v120, v120
	v_exp_f32_e32 v121, v121
	v_exp_f32_e32 v122, v122
	v_exp_f32_e32 v123, v123
	v_exp_f32_e32 v124, v124
	v_exp_f32_e32 v125, v125
	v_add_f32_e32 v120, 1.0, v120
	v_add_f32_e32 v121, 1.0, v121
	v_add_f32_e32 v122, 1.0, v122
	v_add_f32_e32 v123, 1.0, v123
	v_add_f32_e32 v124, 1.0, v124
	v_add_f32_e32 v125, 1.0, v125
	v_rcp_f32_e32 v120, v120
	v_rcp_f32_e32 v121, v121
	v_rcp_f32_e32 v122, v122
	v_rcp_f32_e32 v123, v123
	v_rcp_f32_e32 v124, v124
	v_rcp_f32_e32 v125, v125
	v_mul_f32_e32 v100, v100, v120
	v_mul_f32_e32 v101, v101, v121
	v_mul_f32_e32 v102, v102, v122
	v_mul_f32_e32 v103, v103, v123
	v_mul_f32_e32 v104, v104, v124
	v_mul_f32_e32 v105, v105, v125
	ds_write_b32 v155, v100
	ds_write_b32 v155, v101 offset:2048
	ds_write_b32 v155, v102 offset:4096
	ds_write_b32 v155, v103 offset:6144
	ds_write_b32 v155, v104 offset:8192
	ds_write_b32 v155, v105 offset:10240
	s_waitcnt vmcnt(6)
; __device__ __forceinline__ float siluf(float x) { return x * frcp(1.f + fexp(-x)); }
; __device__ void mods_phase(unsigned char* lds, const Params& p) {
;     ...
;     for (int i = tid; i < 9 * 1024; i += 512) {
;       float v = (i < 8192) ? c[i] : cc[i - 8192];
;       sl[i] = siluf(v);
;     }
;     ...
;     for (int k0 = ks * 64; k0 < ks * 64 + 64; k0 += 16) {
;       float av[16];
; #pragma unroll
;       for (int u = 0; u < 16; ++u) av[u] = aw[(size_t)(k0 + u) * 6144];
	v_mul_f32_e32 v120, 0xbfb8aa3b, v106
	v_mul_f32_e32 v121, 0xbfb8aa3b, v107
	v_mul_f32_e32 v122, 0xbfb8aa3b, v108
	v_mul_f32_e32 v123, 0xbfb8aa3b, v109
	v_mul_f32_e32 v124, 0xbfb8aa3b, v110
	v_mul_f32_e32 v125, 0xbfb8aa3b, v111
	v_exp_f32_e32 v120, v120
	v_exp_f32_e32 v121, v121
	v_exp_f32_e32 v122, v122
	v_exp_f32_e32 v123, v123
	v_exp_f32_e32 v124, v124
	v_exp_f32_e32 v125, v125
	v_add_f32_e32 v120, 1.0, v120
	v_add_f32_e32 v121, 1.0, v121
	v_add_f32_e32 v122, 1.0, v122
	v_add_f32_e32 v123, 1.0, v123
	v_add_f32_e32 v124, 1.0, v124
	v_add_f32_e32 v125, 1.0, v125
	v_rcp_f32_e32 v120, v120
	v_rcp_f32_e32 v121, v121
	v_rcp_f32_e32 v122, v122
	v_rcp_f32_e32 v123, v123
	v_rcp_f32_e32 v124, v124
	v_rcp_f32_e32 v125, v125
	v_mul_f32_e32 v106, v106, v120
	v_mul_f32_e32 v107, v107, v121
	v_mul_f32_e32 v108, v108, v122
	v_mul_f32_e32 v109, v109, v123
	v_mul_f32_e32 v110, v110, v124
	v_mul_f32_e32 v111, v111, v125
	ds_write_b32 v155, v106 offset:12288
	ds_write_b32 v155, v107 offset:14336
	ds_write_b32 v155, v108 offset:16384
	ds_write_b32 v155, v109 offset:18432
	ds_write_b32 v155, v110 offset:20480
	ds_write_b32 v155, v111 offset:22528
	s_waitcnt vmcnt(0)
	v_mul_f32_e32 v120, 0xbfb8aa3b, v112
	v_mul_f32_e32 v121, 0xbfb8aa3b, v113
	v_mul_f32_e32 v122, 0xbfb8aa3b, v114
	v_mul_f32_e32 v123, 0xbfb8aa3b, v115
	v_mul_f32_e32 v124, 0xbfb8aa3b, v116
	v_mul_f32_e32 v125, 0xbfb8aa3b, v117
	v_exp_f32_e32 v120, v120
	v_exp_f32_e32 v121, v121
	v_exp_f32_e32 v122, v122
	v_exp_f32_e32 v123, v123
	v_exp_f32_e32 v124, v124
	v_exp_f32_e32 v125, v125
	v_add_f32_e32 v120, 1.0, v120
	v_add_f32_e32 v121, 1.0, v121
	v_add_f32_e32 v122, 1.0, v122
	v_add_f32_e32 v123, 1.0, v123
	v_add_f32_e32 v124, 1.0, v124
	v_add_f32_e32 v125, 1.0, v125
	v_rcp_f32_e32 v120, v120
	v_rcp_f32_e32 v121, v121
	v_rcp_f32_e32 v122, v122
	v_rcp_f32_e32 v123, v123
	v_rcp_f32_e32 v124, v124
	v_rcp_f32_e32 v125, v125
	v_mul_f32_e32 v112, v112, v120
	v_mul_f32_e32 v113, v113, v121
	v_mul_f32_e32 v114, v114, v122
	v_mul_f32_e32 v115, v115, v123
	v_mul_f32_e32 v116, v116, v124
	v_mul_f32_e32 v117, v117, v125
	ds_write_b32 v155, v112 offset:24576
	ds_write_b32 v155, v113 offset:26624
	ds_write_b32 v155, v114 offset:28672
	ds_write_b32 v155, v115 offset:30720
	ds_write_b32 v155, v116 offset:32768
	ds_write_b32 v155, v117 offset:34816
	global_load_dword v42, v66, s[60:61]
	v_add_u32_e32 v66, 0x6000, v66
	global_load_dword v43, v66, s[60:61]
	v_add_u32_e32 v66, 0x6000, v66
	global_load_dword v44, v66, s[60:61]
	v_add_u32_e32 v66, 0x6000, v66
	global_load_dword v45, v66, s[60:61]
	v_add_u32_e32 v66, 0x6000, v66
	global_load_dword v46, v66, s[60:61]
	v_add_u32_e32 v66, 0x6000, v66
	global_load_dword v47, v66, s[60:61]
	v_add_u32_e32 v66, 0x6000, v66
	global_load_dword v48, v66, s[60:61]
	v_add_u32_e32 v66, 0x6000, v66
	global_load_dword v49, v66, s[60:61]
	v_add_u32_e32 v66, 0x6000, v66
	global_load_dword v50, v66, s[60:61]
	v_add_u32_e32 v66, 0x6000, v66
	global_load_dword v51, v66, s[60:61]
	v_add_u32_e32 v66, 0x6000, v66
	global_load_dword v52, v66, s[60:61]
	v_add_u32_e32 v66, 0x6000, v66
	global_load_dword v53, v66, s[60:61]
	v_add_u32_e32 v66, 0x6000, v66
	global_load_dword v54, v66, s[60:61]
	v_add_u32_e32 v66, 0x6000, v66
	global_load_dword v55, v66, s[60:61]
	v_add_u32_e32 v66, 0x6000, v66
	global_load_dword v56, v66, s[60:61]
	v_add_u32_e32 v66, 0x6000, v66
	global_load_dword v57, v66, s[60:61]
	v_add_u32_e32 v66, 0x6000, v66
	global_load_dword v58, v66, s[60:61]
	v_add_u32_e32 v66, 0x6000, v66
	global_load_dword v59, v66, s[60:61]
	v_add_u32_e32 v66, 0x6000, v66
	global_load_dword v60, v66, s[60:61]
	v_add_u32_e32 v66, 0x6000, v66
	global_load_dword v61, v66, s[60:61]
	v_add_u32_e32 v66, 0x6000, v66
	global_load_dword v62, v66, s[60:61]
	v_add_u32_e32 v66, 0x6000, v66
	global_load_dword v63, v66, s[60:61]
	v_add_u32_e32 v66, 0x6000, v66
	global_load_dword v64, v66, s[60:61]
	v_add_u32_e32 v66, 0x6000, v66
	global_load_dword v65, v66, s[60:61]
	v_add_u32_e32 v66, 0x6000, v66
.LBB0_11:
	s_or_b64 exec, exec, s[16:17]
	s_mul_hi_i32 s4, s40, 0x2aaaaaab
	s_lshr_b32 s5, s4, 31
	s_ashr_i32 s4, s4, 5
	s_add_i32 s41, s4, s5
	s_mul_i32 s4, s41, 0xc0
	s_sub_i32 s4, s40, s4
	s_lshl_b32 s4, s4, 5
	s_ashr_i32 s5, s4, 31
	s_mul_i32 s19, s41, 0x1800000
	s_lshl_b64 s[16:17], s[4:5], 2
	s_mul_hi_i32 s18, s41, 0x1800000
	s_add_u32 s4, s19, s16
	s_addc_u32 s5, s18, s17
	v_mov_b32_e32 v190, 0
	v_lshl_add_u64 v[144:145], v[140:141], 0, s[4:5]
	s_mov_b64 s[18:19], 0
	v_mov_b32_e32 v143, v186
	v_mov_b32_e32 v189, v135
	v_mov_b32_e32 v146, 0
	v_mov_b32_e32 v147, v190
	v_mov_b32_e32 v148, 0
	v_mov_b32_e32 v149, v190
	v_mov_b32_e32 v150, 0
	v_mov_b32_e32 v151, v190
	v_mov_b32_e32 v152, 0
	v_mov_b32_e32 v153, v190
	s_waitcnt lgkmcnt(0)
	s_barrier
; __device__ void mods_phase(unsigned char* lds, const Params& p) {
;     ...
;     for (int k0 = ks * 64; k0 < ks * 64 + 64; k0 += 16) {
;       float av[16];
; #pragma unroll
;       for (int u = 0; u < 16; ++u) av[u] = aw[(size_t)(k0 + u) * 6144];
; #pragma unroll
;       for (int u = 0; u < 16; ++u)
; #pragma unroll
;         for (int r = 0; r < 9; ++r) acc[r] += sl[r * 1024 + k0 + u] * av[u];
;     }
	v_mov_b32_e32 v156, 0
	v_mov_b32_e32 v157, 0
	v_mov_b32_e32 v158, 0
	v_mov_b32_e32 v159, 0
	v_mov_b32_e32 v160, 0
	v_mov_b32_e32 v161, 0
	v_mov_b32_e32 v162, 0
	v_mov_b32_e32 v163, 0
	v_mov_b32_e32 v164, 0
	v_mov_b32_e32 v165, 0
	v_mov_b32_e32 v166, 0
	v_mov_b32_e32 v167, 0
	v_mov_b32_e32 v168, 0
	v_mov_b32_e32 v169, 0
	v_mov_b32_e32 v170, 0
	v_mov_b32_e32 v171, 0
	v_mov_b32_e32 v172, 0
	v_mov_b32_e32 v173, 0
	s_waitcnt vmcnt(0)
	ds_read_b128 v[68:71], v186 offset:0
	ds_read_b128 v[72:75], v186 offset:16
	ds_read_b128 v[76:79], v186 offset:32
	ds_read_b128 v[80:83], v186 offset:48
	ds_read_b128 v[84:87], v186 offset:64
	ds_read_b128 v[88:91], v186 offset:80
	ds_read_b128 v[92:95], v186 offset:96
	ds_read_b128 v[96:99], v186 offset:112
	ds_read_b128 v[100:103], v186 offset:128
	ds_read_b128 v[104:107], v186 offset:144
	ds_read_b128 v[108:111], v186 offset:160
	ds_read_b128 v[112:115], v186 offset:176
	s_waitcnt lgkmcnt(8)
	v_pk_fma_f32 v[156:157], v[68:69], v[2:3], v[156:157]
	v_pk_fma_f32 v[156:157], v[70:71], v[4:5], v[156:157]
	v_pk_fma_f32 v[156:157], v[72:73], v[6:7], v[156:157]
	v_pk_fma_f32 v[156:157], v[74:75], v[8:9], v[156:157]
	v_pk_fma_f32 v[156:157], v[76:77], v[10:11], v[156:157]
	v_pk_fma_f32 v[156:157], v[78:79], v[12:13], v[156:157]
	v_pk_fma_f32 v[156:157], v[80:81], v[14:15], v[156:157]
	v_pk_fma_f32 v[156:157], v[82:83], v[16:17], v[156:157]
	ds_read_b128 v[68:71], v186 offset:192
	ds_read_b128 v[72:75], v186 offset:208
	ds_read_b128 v[76:79], v186 offset:224
	ds_read_b128 v[80:83], v186 offset:240
	s_waitcnt lgkmcnt(8)
	v_pk_fma_f32 v[156:157], v[84:85], v[18:19], v[156:157]
	v_pk_fma_f32 v[156:157], v[86:87], v[20:21], v[156:157]
	v_pk_fma_f32 v[156:157], v[88:89], v[22:23], v[156:157]
	v_pk_fma_f32 v[156:157], v[90:91], v[24:25], v[156:157]
	v_pk_fma_f32 v[156:157], v[92:93], v[26:27], v[156:157]
	v_pk_fma_f32 v[156:157], v[94:95], v[28:29], v[156:157]
	v_pk_fma_f32 v[156:157], v[96:97], v[30:31], v[156:157]
	v_pk_fma_f32 v[156:157], v[98:99], v[32:33], v[156:157]
	ds_read_b128 v[84:87], v186 offset:4096
	ds_read_b128 v[88:91], v186 offset:4112
	ds_read_b128 v[92:95], v186 offset:4128
	ds_read_b128 v[96:99], v186 offset:4144
	s_waitcnt lgkmcnt(8)
	v_pk_fma_f32 v[156:157], v[100:101], v[34:35], v[156:157]
	v_pk_fma_f32 v[156:157], v[102:103], v[36:37], v[156:157]
	v_pk_fma_f32 v[156:157], v[104:105], v[38:39], v[156:157]
	v_pk_fma_f32 v[156:157], v[106:107], v[40:41], v[156:157]
	v_pk_fma_f32 v[156:157], v[108:109], v[42:43], v[156:157]
	v_pk_fma_f32 v[156:157], v[110:111], v[44:45], v[156:157]
	v_pk_fma_f32 v[156:157], v[112:113], v[46:47], v[156:157]
	v_pk_fma_f32 v[156:157], v[114:115], v[48:49], v[156:157]
	ds_read_b128 v[100:103], v186 offset:4160
	ds_read_b128 v[104:107], v186 offset:4176
	ds_read_b128 v[108:111], v186 offset:4192
	ds_read_b128 v[112:115], v186 offset:4208
	s_waitcnt lgkmcnt(8)
	v_pk_fma_f32 v[156:157], v[68:69], v[50:51], v[156:157]
	v_pk_fma_f32 v[156:157], v[70:71], v[52:53], v[156:157]
	v_pk_fma_f32 v[156:157], v[72:73], v[54:55], v[156:157]
	v_pk_fma_f32 v[156:157], v[74:75], v[56:57], v[156:157]
	v_pk_fma_f32 v[156:157], v[76:77], v[58:59], v[156:157]
	v_pk_fma_f32 v[156:157], v[78:79], v[60:61], v[156:157]
	v_pk_fma_f32 v[156:157], v[80:81], v[62:63], v[156:157]
	v_pk_fma_f32 v[156:157], v[82:83], v[64:65], v[156:157]
	ds_read_b128 v[68:71], v186 offset:4224
	ds_read_b128 v[72:75], v186 offset:4240
	ds_read_b128 v[76:79], v186 offset:4256
	ds_read_b128 v[80:83], v186 offset:4272
	s_waitcnt lgkmcnt(8)
	v_pk_fma_f32 v[158:159], v[84:85], v[2:3], v[158:159]
	v_pk_fma_f32 v[158:159], v[86:87], v[4:5], v[158:159]
	v_pk_fma_f32 v[158:159], v[88:89], v[6:7], v[158:159]
	v_pk_fma_f32 v[158:159], v[90:91], v[8:9], v[158:159]
	v_pk_fma_f32 v[158:159], v[92:93], v[10:11], v[158:159]
	v_pk_fma_f32 v[158:159], v[94:95], v[12:13], v[158:159]
	v_pk_fma_f32 v[158:159], v[96:97], v[14:15], v[158:159]
	v_pk_fma_f32 v[158:159], v[98:99], v[16:17], v[158:159]
	ds_read_b128 v[84:87], v186 offset:4288
	ds_read_b128 v[88:91], v186 offset:4304
	ds_read_b128 v[92:95], v186 offset:4320
	ds_read_b128 v[96:99], v186 offset:4336
	s_waitcnt lgkmcnt(8)
	v_pk_fma_f32 v[158:159], v[100:101], v[18:19], v[158:159]
	v_pk_fma_f32 v[158:159], v[102:103], v[20:21], v[158:159]
	v_pk_fma_f32 v[158:159], v[104:105], v[22:23], v[158:159]
	v_pk_fma_f32 v[158:159], v[106:107], v[24:25], v[158:159]
	v_pk_fma_f32 v[158:159], v[108:109], v[26:27], v[158:159]
	v_pk_fma_f32 v[158:159], v[110:111], v[28:29], v[158:159]
	v_pk_fma_f32 v[158:159], v[112:113], v[30:31], v[158:159]
	v_pk_fma_f32 v[158:159], v[114:115], v[32:33], v[158:159]
	ds_read_b128 v[100:103], v186 offset:8192
	ds_read_b128 v[104:107], v186 offset:8208
	ds_read_b128 v[108:111], v186 offset:8224
	ds_read_b128 v[112:115], v186 offset:8240
	s_waitcnt lgkmcnt(8)
	v_pk_fma_f32 v[158:159], v[68:69], v[34:35], v[158:159]
	v_pk_fma_f32 v[158:159], v[70:71], v[36:37], v[158:159]
	v_pk_fma_f32 v[158:159], v[72:73], v[38:39], v[158:159]
	v_pk_fma_f32 v[158:159], v[74:75], v[40:41], v[158:159]
	v_pk_fma_f32 v[158:159], v[76:77], v[42:43], v[158:159]
	v_pk_fma_f32 v[158:159], v[78:79], v[44:45], v[158:159]
	v_pk_fma_f32 v[158:159], v[80:81], v[46:47], v[158:159]
	v_pk_fma_f32 v[158:159], v[82:83], v[48:49], v[158:159]
	ds_read_b128 v[68:71], v186 offset:8256
	ds_read_b128 v[72:75], v186 offset:8272
	ds_read_b128 v[76:79], v186 offset:8288
	ds_read_b128 v[80:83], v186 offset:8304
	s_waitcnt lgkmcnt(8)
; __device__ void mods_phase(unsigned char* lds, const Params& p) {
;     ...
;     for (int k0 = ks * 64; k0 < ks * 64 + 64; k0 += 16) {
;       float av[16];
; #pragma unroll
;       for (int u = 0; u < 16; ++u) av[u] = aw[(size_t)(k0 + u) * 6144];
; #pragma unroll
;       for (int u = 0; u < 16; ++u)
; #pragma unroll
;         for (int r = 0; r < 9; ++r) acc[r] += sl[r * 1024 + k0 + u] * av[u];
;     }
	v_pk_fma_f32 v[158:159], v[84:85], v[50:51], v[158:159]
	v_pk_fma_f32 v[158:159], v[86:87], v[52:53], v[158:159]
	v_pk_fma_f32 v[158:159], v[88:89], v[54:55], v[158:159]
	v_pk_fma_f32 v[158:159], v[90:91], v[56:57], v[158:159]
	v_pk_fma_f32 v[158:159], v[92:93], v[58:59], v[158:159]
	v_pk_fma_f32 v[158:159], v[94:95], v[60:61], v[158:159]
	v_pk_fma_f32 v[158:159], v[96:97], v[62:63], v[158:159]
	v_pk_fma_f32 v[158:159], v[98:99], v[64:65], v[158:159]
	ds_read_b128 v[84:87], v186 offset:8320
	ds_read_b128 v[88:91], v186 offset:8336
	ds_read_b128 v[92:95], v186 offset:8352
	ds_read_b128 v[96:99], v186 offset:8368
	s_waitcnt lgkmcnt(8)
	v_pk_fma_f32 v[160:161], v[100:101], v[2:3], v[160:161]
	v_pk_fma_f32 v[160:161], v[102:103], v[4:5], v[160:161]
	v_pk_fma_f32 v[160:161], v[104:105], v[6:7], v[160:161]
	v_pk_fma_f32 v[160:161], v[106:107], v[8:9], v[160:161]
	v_pk_fma_f32 v[160:161], v[108:109], v[10:11], v[160:161]
	v_pk_fma_f32 v[160:161], v[110:111], v[12:13], v[160:161]
	v_pk_fma_f32 v[160:161], v[112:113], v[14:15], v[160:161]
	v_pk_fma_f32 v[160:161], v[114:115], v[16:17], v[160:161]
	ds_read_b128 v[100:103], v186 offset:8384
	ds_read_b128 v[104:107], v186 offset:8400
	ds_read_b128 v[108:111], v186 offset:8416
	ds_read_b128 v[112:115], v186 offset:8432
	s_waitcnt lgkmcnt(8)
	v_pk_fma_f32 v[160:161], v[68:69], v[18:19], v[160:161]
	v_pk_fma_f32 v[160:161], v[70:71], v[20:21], v[160:161]
	v_pk_fma_f32 v[160:161], v[72:73], v[22:23], v[160:161]
	v_pk_fma_f32 v[160:161], v[74:75], v[24:25], v[160:161]
	v_pk_fma_f32 v[160:161], v[76:77], v[26:27], v[160:161]
	v_pk_fma_f32 v[160:161], v[78:79], v[28:29], v[160:161]
	v_pk_fma_f32 v[160:161], v[80:81], v[30:31], v[160:161]
	v_pk_fma_f32 v[160:161], v[82:83], v[32:33], v[160:161]
	ds_read_b128 v[68:71], v186 offset:12288
	ds_read_b128 v[72:75], v186 offset:12304
	ds_read_b128 v[76:79], v186 offset:12320
	ds_read_b128 v[80:83], v186 offset:12336
	s_waitcnt lgkmcnt(8)
	v_pk_fma_f32 v[160:161], v[84:85], v[34:35], v[160:161]
	v_pk_fma_f32 v[160:161], v[86:87], v[36:37], v[160:161]
	v_pk_fma_f32 v[160:161], v[88:89], v[38:39], v[160:161]
	v_pk_fma_f32 v[160:161], v[90:91], v[40:41], v[160:161]
	v_pk_fma_f32 v[160:161], v[92:93], v[42:43], v[160:161]
	v_pk_fma_f32 v[160:161], v[94:95], v[44:45], v[160:161]
	v_pk_fma_f32 v[160:161], v[96:97], v[46:47], v[160:161]
	v_pk_fma_f32 v[160:161], v[98:99], v[48:49], v[160:161]
	ds_read_b128 v[84:87], v186 offset:12352
	ds_read_b128 v[88:91], v186 offset:12368
	ds_read_b128 v[92:95], v186 offset:12384
	ds_read_b128 v[96:99], v186 offset:12400
	s_waitcnt lgkmcnt(8)
	v_pk_fma_f32 v[160:161], v[100:101], v[50:51], v[160:161]
	v_pk_fma_f32 v[160:161], v[102:103], v[52:53], v[160:161]
	v_pk_fma_f32 v[160:161], v[104:105], v[54:55], v[160:161]
	v_pk_fma_f32 v[160:161], v[106:107], v[56:57], v[160:161]
	v_pk_fma_f32 v[160:161], v[108:109], v[58:59], v[160:161]
	v_pk_fma_f32 v[160:161], v[110:111], v[60:61], v[160:161]
	v_pk_fma_f32 v[160:161], v[112:113], v[62:63], v[160:161]
	v_pk_fma_f32 v[160:161], v[114:115], v[64:65], v[160:161]
	ds_read_b128 v[100:103], v186 offset:12416
	ds_read_b128 v[104:107], v186 offset:12432
	ds_read_b128 v[108:111], v186 offset:12448
	ds_read_b128 v[112:115], v186 offset:12464
	s_waitcnt lgkmcnt(8)
	v_pk_fma_f32 v[162:163], v[68:69], v[2:3], v[162:163]
	v_pk_fma_f32 v[162:163], v[70:71], v[4:5], v[162:163]
	v_pk_fma_f32 v[162:163], v[72:73], v[6:7], v[162:163]
	v_pk_fma_f32 v[162:163], v[74:75], v[8:9], v[162:163]
	v_pk_fma_f32 v[162:163], v[76:77], v[10:11], v[162:163]
	v_pk_fma_f32 v[162:163], v[78:79], v[12:13], v[162:163]
	v_pk_fma_f32 v[162:163], v[80:81], v[14:15], v[162:163]
	v_pk_fma_f32 v[162:163], v[82:83], v[16:17], v[162:163]
	ds_read_b128 v[68:71], v186 offset:12480
	ds_read_b128 v[72:75], v186 offset:12496
	ds_read_b128 v[76:79], v186 offset:12512
	ds_read_b128 v[80:83], v186 offset:12528
	s_waitcnt lgkmcnt(8)
	v_pk_fma_f32 v[162:163], v[84:85], v[18:19], v[162:163]
	v_pk_fma_f32 v[162:163], v[86:87], v[20:21], v[162:163]
	v_pk_fma_f32 v[162:163], v[88:89], v[22:23], v[162:163]
	v_pk_fma_f32 v[162:163], v[90:91], v[24:25], v[162:163]
	v_pk_fma_f32 v[162:163], v[92:93], v[26:27], v[162:163]
	v_pk_fma_f32 v[162:163], v[94:95], v[28:29], v[162:163]
	v_pk_fma_f32 v[162:163], v[96:97], v[30:31], v[162:163]
	v_pk_fma_f32 v[162:163], v[98:99], v[32:33], v[162:163]
	ds_read_b128 v[84:87], v186 offset:16384
	ds_read_b128 v[88:91], v186 offset:16400
	ds_read_b128 v[92:95], v186 offset:16416
	ds_read_b128 v[96:99], v186 offset:16432
	s_waitcnt lgkmcnt(8)
	v_pk_fma_f32 v[162:163], v[100:101], v[34:35], v[162:163]
	v_pk_fma_f32 v[162:163], v[102:103], v[36:37], v[162:163]
	v_pk_fma_f32 v[162:163], v[104:105], v[38:39], v[162:163]
	v_pk_fma_f32 v[162:163], v[106:107], v[40:41], v[162:163]
	v_pk_fma_f32 v[162:163], v[108:109], v[42:43], v[162:163]
	v_pk_fma_f32 v[162:163], v[110:111], v[44:45], v[162:163]
	v_pk_fma_f32 v[162:163], v[112:113], v[46:47], v[162:163]
	v_pk_fma_f32 v[162:163], v[114:115], v[48:49], v[162:163]
	ds_read_b128 v[100:103], v186 offset:16448
	ds_read_b128 v[104:107], v186 offset:16464
	ds_read_b128 v[108:111], v186 offset:16480
	ds_read_b128 v[112:115], v186 offset:16496
	s_waitcnt lgkmcnt(8)
	v_pk_fma_f32 v[162:163], v[68:69], v[50:51], v[162:163]
	v_pk_fma_f32 v[162:163], v[70:71], v[52:53], v[162:163]
	v_pk_fma_f32 v[162:163], v[72:73], v[54:55], v[162:163]
	v_pk_fma_f32 v[162:163], v[74:75], v[56:57], v[162:163]
	v_pk_fma_f32 v[162:163], v[76:77], v[58:59], v[162:163]
	v_pk_fma_f32 v[162:163], v[78:79], v[60:61], v[162:163]
	v_pk_fma_f32 v[162:163], v[80:81], v[62:63], v[162:163]
	v_pk_fma_f32 v[162:163], v[82:83], v[64:65], v[162:163]
	ds_read_b128 v[68:71], v186 offset:16512
	ds_read_b128 v[72:75], v186 offset:16528
	ds_read_b128 v[76:79], v186 offset:16544
	ds_read_b128 v[80:83], v186 offset:16560
	s_waitcnt lgkmcnt(8)
; __device__ void mods_phase(unsigned char* lds, const Params& p) {
;     ...
;     for (int k0 = ks * 64; k0 < ks * 64 + 64; k0 += 16) {
;       float av[16];
; #pragma unroll
;       for (int u = 0; u < 16; ++u) av[u] = aw[(size_t)(k0 + u) * 6144];
; #pragma unroll
;       for (int u = 0; u < 16; ++u)
; #pragma unroll
;         for (int r = 0; r < 9; ++r) acc[r] += sl[r * 1024 + k0 + u] * av[u];
;     }
	v_pk_fma_f32 v[164:165], v[84:85], v[2:3], v[164:165]
	v_pk_fma_f32 v[164:165], v[86:87], v[4:5], v[164:165]
	v_pk_fma_f32 v[164:165], v[88:89], v[6:7], v[164:165]
	v_pk_fma_f32 v[164:165], v[90:91], v[8:9], v[164:165]
	v_pk_fma_f32 v[164:165], v[92:93], v[10:11], v[164:165]
	v_pk_fma_f32 v[164:165], v[94:95], v[12:13], v[164:165]
	v_pk_fma_f32 v[164:165], v[96:97], v[14:15], v[164:165]
	v_pk_fma_f32 v[164:165], v[98:99], v[16:17], v[164:165]
	ds_read_b128 v[84:87], v186 offset:16576
	ds_read_b128 v[88:91], v186 offset:16592
	ds_read_b128 v[92:95], v186 offset:16608
	ds_read_b128 v[96:99], v186 offset:16624
	s_waitcnt lgkmcnt(8)
	v_pk_fma_f32 v[164:165], v[100:101], v[18:19], v[164:165]
	v_pk_fma_f32 v[164:165], v[102:103], v[20:21], v[164:165]
	v_pk_fma_f32 v[164:165], v[104:105], v[22:23], v[164:165]
	v_pk_fma_f32 v[164:165], v[106:107], v[24:25], v[164:165]
	v_pk_fma_f32 v[164:165], v[108:109], v[26:27], v[164:165]
	v_pk_fma_f32 v[164:165], v[110:111], v[28:29], v[164:165]
	v_pk_fma_f32 v[164:165], v[112:113], v[30:31], v[164:165]
	v_pk_fma_f32 v[164:165], v[114:115], v[32:33], v[164:165]
	ds_read_b128 v[100:103], v186 offset:20480
	ds_read_b128 v[104:107], v186 offset:20496
	ds_read_b128 v[108:111], v186 offset:20512
	ds_read_b128 v[112:115], v186 offset:20528
	s_waitcnt lgkmcnt(8)
	v_pk_fma_f32 v[164:165], v[68:69], v[34:35], v[164:165]
	v_pk_fma_f32 v[164:165], v[70:71], v[36:37], v[164:165]
	v_pk_fma_f32 v[164:165], v[72:73], v[38:39], v[164:165]
	v_pk_fma_f32 v[164:165], v[74:75], v[40:41], v[164:165]
	v_pk_fma_f32 v[164:165], v[76:77], v[42:43], v[164:165]
	v_pk_fma_f32 v[164:165], v[78:79], v[44:45], v[164:165]
	v_pk_fma_f32 v[164:165], v[80:81], v[46:47], v[164:165]
	v_pk_fma_f32 v[164:165], v[82:83], v[48:49], v[164:165]
	ds_read_b128 v[68:71], v186 offset:20544
	ds_read_b128 v[72:75], v186 offset:20560
	ds_read_b128 v[76:79], v186 offset:20576
	ds_read_b128 v[80:83], v186 offset:20592
	s_waitcnt lgkmcnt(8)
	v_pk_fma_f32 v[164:165], v[84:85], v[50:51], v[164:165]
	v_pk_fma_f32 v[164:165], v[86:87], v[52:53], v[164:165]
	v_pk_fma_f32 v[164:165], v[88:89], v[54:55], v[164:165]
	v_pk_fma_f32 v[164:165], v[90:91], v[56:57], v[164:165]
	v_pk_fma_f32 v[164:165], v[92:93], v[58:59], v[164:165]
	v_pk_fma_f32 v[164:165], v[94:95], v[60:61], v[164:165]
	v_pk_fma_f32 v[164:165], v[96:97], v[62:63], v[164:165]
	v_pk_fma_f32 v[164:165], v[98:99], v[64:65], v[164:165]
	ds_read_b128 v[84:87], v186 offset:20608
	ds_read_b128 v[88:91], v186 offset:20624
	ds_read_b128 v[92:95], v186 offset:20640
	ds_read_b128 v[96:99], v186 offset:20656
	s_waitcnt lgkmcnt(8)
	v_pk_fma_f32 v[166:167], v[100:101], v[2:3], v[166:167]
	v_pk_fma_f32 v[166:167], v[102:103], v[4:5], v[166:167]
	v_pk_fma_f32 v[166:167], v[104:105], v[6:7], v[166:167]
	v_pk_fma_f32 v[166:167], v[106:107], v[8:9], v[166:167]
	v_pk_fma_f32 v[166:167], v[108:109], v[10:11], v[166:167]
	v_pk_fma_f32 v[166:167], v[110:111], v[12:13], v[166:167]
	v_pk_fma_f32 v[166:167], v[112:113], v[14:15], v[166:167]
	v_pk_fma_f32 v[166:167], v[114:115], v[16:17], v[166:167]
	ds_read_b128 v[100:103], v186 offset:20672
	ds_read_b128 v[104:107], v186 offset:20688
	ds_read_b128 v[108:111], v186 offset:20704
	ds_read_b128 v[112:115], v186 offset:20720
	s_waitcnt lgkmcnt(8)
	v_pk_fma_f32 v[166:167], v[68:69], v[18:19], v[166:167]
	v_pk_fma_f32 v[166:167], v[70:71], v[20:21], v[166:167]
	v_pk_fma_f32 v[166:167], v[72:73], v[22:23], v[166:167]
	v_pk_fma_f32 v[166:167], v[74:75], v[24:25], v[166:167]
	v_pk_fma_f32 v[166:167], v[76:77], v[26:27], v[166:167]
	v_pk_fma_f32 v[166:167], v[78:79], v[28:29], v[166:167]
	v_pk_fma_f32 v[166:167], v[80:81], v[30:31], v[166:167]
	v_pk_fma_f32 v[166:167], v[82:83], v[32:33], v[166:167]
	ds_read_b128 v[68:71], v186 offset:24576
	ds_read_b128 v[72:75], v186 offset:24592
	ds_read_b128 v[76:79], v186 offset:24608
	ds_read_b128 v[80:83], v186 offset:24624
	s_waitcnt lgkmcnt(8)
	v_pk_fma_f32 v[166:167], v[84:85], v[34:35], v[166:167]
	v_pk_fma_f32 v[166:167], v[86:87], v[36:37], v[166:167]
	v_pk_fma_f32 v[166:167], v[88:89], v[38:39], v[166:167]
	v_pk_fma_f32 v[166:167], v[90:91], v[40:41], v[166:167]
	v_pk_fma_f32 v[166:167], v[92:93], v[42:43], v[166:167]
	v_pk_fma_f32 v[166:167], v[94:95], v[44:45], v[166:167]
	v_pk_fma_f32 v[166:167], v[96:97], v[46:47], v[166:167]
	v_pk_fma_f32 v[166:167], v[98:99], v[48:49], v[166:167]
	ds_read_b128 v[84:87], v186 offset:24640
	ds_read_b128 v[88:91], v186 offset:24656
	ds_read_b128 v[92:95], v186 offset:24672
	ds_read_b128 v[96:99], v186 offset:24688
	s_waitcnt lgkmcnt(8)
	v_pk_fma_f32 v[166:167], v[100:101], v[50:51], v[166:167]
	v_pk_fma_f32 v[166:167], v[102:103], v[52:53], v[166:167]
	v_pk_fma_f32 v[166:167], v[104:105], v[54:55], v[166:167]
	v_pk_fma_f32 v[166:167], v[106:107], v[56:57], v[166:167]
	v_pk_fma_f32 v[166:167], v[108:109], v[58:59], v[166:167]
	v_pk_fma_f32 v[166:167], v[110:111], v[60:61], v[166:167]
	v_pk_fma_f32 v[166:167], v[112:113], v[62:63], v[166:167]
	v_pk_fma_f32 v[166:167], v[114:115], v[64:65], v[166:167]
	ds_read_b128 v[100:103], v186 offset:24704
	ds_read_b128 v[104:107], v186 offset:24720
	ds_read_b128 v[108:111], v186 offset:24736
	ds_read_b128 v[112:115], v186 offset:24752
	s_waitcnt lgkmcnt(8)
	v_pk_fma_f32 v[168:169], v[68:69], v[2:3], v[168:169]
	v_pk_fma_f32 v[168:169], v[70:71], v[4:5], v[168:169]
	v_pk_fma_f32 v[168:169], v[72:73], v[6:7], v[168:169]
	v_pk_fma_f32 v[168:169], v[74:75], v[8:9], v[168:169]
	v_pk_fma_f32 v[168:169], v[76:77], v[10:11], v[168:169]
	v_pk_fma_f32 v[168:169], v[78:79], v[12:13], v[168:169]
	v_pk_fma_f32 v[168:169], v[80:81], v[14:15], v[168:169]
	v_pk_fma_f32 v[168:169], v[82:83], v[16:17], v[168:169]
	ds_read_b128 v[68:71], v186 offset:24768
	ds_read_b128 v[72:75], v186 offset:24784
	ds_read_b128 v[76:79], v186 offset:24800
	ds_read_b128 v[80:83], v186 offset:24816
	s_waitcnt lgkmcnt(8)
; __device__ void mods_phase(unsigned char* lds, const Params& p) {
;     ...
;     for (int k0 = ks * 64; k0 < ks * 64 + 64; k0 += 16) {
;       float av[16];
; #pragma unroll
;       for (int u = 0; u < 16; ++u) av[u] = aw[(size_t)(k0 + u) * 6144];
; #pragma unroll
;       for (int u = 0; u < 16; ++u)
; #pragma unroll
;         for (int r = 0; r < 9; ++r) acc[r] += sl[r * 1024 + k0 + u] * av[u];
;     }
	v_pk_fma_f32 v[168:169], v[84:85], v[18:19], v[168:169]
	v_pk_fma_f32 v[168:169], v[86:87], v[20:21], v[168:169]
	v_pk_fma_f32 v[168:169], v[88:89], v[22:23], v[168:169]
	v_pk_fma_f32 v[168:169], v[90:91], v[24:25], v[168:169]
	v_pk_fma_f32 v[168:169], v[92:93], v[26:27], v[168:169]
	v_pk_fma_f32 v[168:169], v[94:95], v[28:29], v[168:169]
	v_pk_fma_f32 v[168:169], v[96:97], v[30:31], v[168:169]
	v_pk_fma_f32 v[168:169], v[98:99], v[32:33], v[168:169]
	ds_read_b128 v[84:87], v186 offset:28672
	ds_read_b128 v[88:91], v186 offset:28688
	ds_read_b128 v[92:95], v186 offset:28704
	ds_read_b128 v[96:99], v186 offset:28720
	s_waitcnt lgkmcnt(8)
	v_pk_fma_f32 v[168:169], v[100:101], v[34:35], v[168:169]
	v_pk_fma_f32 v[168:169], v[102:103], v[36:37], v[168:169]
	v_pk_fma_f32 v[168:169], v[104:105], v[38:39], v[168:169]
	v_pk_fma_f32 v[168:169], v[106:107], v[40:41], v[168:169]
	v_pk_fma_f32 v[168:169], v[108:109], v[42:43], v[168:169]
	v_pk_fma_f32 v[168:169], v[110:111], v[44:45], v[168:169]
	v_pk_fma_f32 v[168:169], v[112:113], v[46:47], v[168:169]
	v_pk_fma_f32 v[168:169], v[114:115], v[48:49], v[168:169]
	ds_read_b128 v[100:103], v186 offset:28736
	ds_read_b128 v[104:107], v186 offset:28752
	ds_read_b128 v[108:111], v186 offset:28768
	ds_read_b128 v[112:115], v186 offset:28784
	s_waitcnt lgkmcnt(8)
	v_pk_fma_f32 v[168:169], v[68:69], v[50:51], v[168:169]
	v_pk_fma_f32 v[168:169], v[70:71], v[52:53], v[168:169]
	v_pk_fma_f32 v[168:169], v[72:73], v[54:55], v[168:169]
	v_pk_fma_f32 v[168:169], v[74:75], v[56:57], v[168:169]
	v_pk_fma_f32 v[168:169], v[76:77], v[58:59], v[168:169]
	v_pk_fma_f32 v[168:169], v[78:79], v[60:61], v[168:169]
	v_pk_fma_f32 v[168:169], v[80:81], v[62:63], v[168:169]
	v_pk_fma_f32 v[168:169], v[82:83], v[64:65], v[168:169]
	ds_read_b128 v[68:71], v186 offset:28800
	ds_read_b128 v[72:75], v186 offset:28816
	ds_read_b128 v[76:79], v186 offset:28832
	ds_read_b128 v[80:83], v186 offset:28848
	s_waitcnt lgkmcnt(8)
	v_pk_fma_f32 v[170:171], v[84:85], v[2:3], v[170:171]
	v_pk_fma_f32 v[170:171], v[86:87], v[4:5], v[170:171]
	v_pk_fma_f32 v[170:171], v[88:89], v[6:7], v[170:171]
	v_pk_fma_f32 v[170:171], v[90:91], v[8:9], v[170:171]
	v_pk_fma_f32 v[170:171], v[92:93], v[10:11], v[170:171]
	v_pk_fma_f32 v[170:171], v[94:95], v[12:13], v[170:171]
	v_pk_fma_f32 v[170:171], v[96:97], v[14:15], v[170:171]
	v_pk_fma_f32 v[170:171], v[98:99], v[16:17], v[170:171]
	ds_read_b128 v[84:87], v186 offset:28864
	ds_read_b128 v[88:91], v186 offset:28880
	ds_read_b128 v[92:95], v186 offset:28896
	ds_read_b128 v[96:99], v186 offset:28912
	s_waitcnt lgkmcnt(8)
	v_pk_fma_f32 v[170:171], v[100:101], v[18:19], v[170:171]
	v_pk_fma_f32 v[170:171], v[102:103], v[20:21], v[170:171]
	v_pk_fma_f32 v[170:171], v[104:105], v[22:23], v[170:171]
	v_pk_fma_f32 v[170:171], v[106:107], v[24:25], v[170:171]
	v_pk_fma_f32 v[170:171], v[108:109], v[26:27], v[170:171]
	v_pk_fma_f32 v[170:171], v[110:111], v[28:29], v[170:171]
	v_pk_fma_f32 v[170:171], v[112:113], v[30:31], v[170:171]
	v_pk_fma_f32 v[170:171], v[114:115], v[32:33], v[170:171]
	ds_read_b128 v[100:103], v186 offset:32768
	ds_read_b128 v[104:107], v186 offset:32784
	ds_read_b128 v[108:111], v186 offset:32800
	ds_read_b128 v[112:115], v186 offset:32816
	s_waitcnt lgkmcnt(8)
	v_pk_fma_f32 v[170:171], v[68:69], v[34:35], v[170:171]
	v_pk_fma_f32 v[170:171], v[70:71], v[36:37], v[170:171]
	v_pk_fma_f32 v[170:171], v[72:73], v[38:39], v[170:171]
	v_pk_fma_f32 v[170:171], v[74:75], v[40:41], v[170:171]
	v_pk_fma_f32 v[170:171], v[76:77], v[42:43], v[170:171]
	v_pk_fma_f32 v[170:171], v[78:79], v[44:45], v[170:171]
	v_pk_fma_f32 v[170:171], v[80:81], v[46:47], v[170:171]
	v_pk_fma_f32 v[170:171], v[82:83], v[48:49], v[170:171]
	ds_read_b128 v[68:71], v186 offset:32832
	ds_read_b128 v[72:75], v186 offset:32848
	ds_read_b128 v[76:79], v186 offset:32864
	ds_read_b128 v[80:83], v186 offset:32880
	s_waitcnt lgkmcnt(8)
	v_pk_fma_f32 v[170:171], v[84:85], v[50:51], v[170:171]
	v_pk_fma_f32 v[170:171], v[86:87], v[52:53], v[170:171]
	v_pk_fma_f32 v[170:171], v[88:89], v[54:55], v[170:171]
	v_pk_fma_f32 v[170:171], v[90:91], v[56:57], v[170:171]
	v_pk_fma_f32 v[170:171], v[92:93], v[58:59], v[170:171]
	v_pk_fma_f32 v[170:171], v[94:95], v[60:61], v[170:171]
	v_pk_fma_f32 v[170:171], v[96:97], v[62:63], v[170:171]
	v_pk_fma_f32 v[170:171], v[98:99], v[64:65], v[170:171]
	ds_read_b128 v[84:87], v186 offset:32896
	ds_read_b128 v[88:91], v186 offset:32912
	ds_read_b128 v[92:95], v186 offset:32928
	ds_read_b128 v[96:99], v186 offset:32944
	s_waitcnt lgkmcnt(8)
; __device__ void mods_phase(unsigned char* lds, const Params& p) {
;     ...
; #pragma unroll
;       for (int u = 0; u < 16; ++u)
; #pragma unroll
;         for (int r = 0; r < 9; ++r) acc[r] += sl[r * 1024 + k0 + u] * av[u];
;     }
; #pragma unroll
;     for (int r = 0; r < 9; ++r) red[(ks * 9 + r) * 32 + cl] = acc[r];
;     __syncthreads();
;     if (tid < 288) {
;       const int r = tid >> 5, c2 = tid & 31;
;       float s = 0.f;
;       for (int q = 0; q < 16; ++q) s += red[(q * 9 + r) * 32 + c2];
;       mod[((size_t)l * 9 + r) * 6144 + cb + c2] = s + p.in[5][(size_t)l * 6144 + cb + c2];
;     }
	v_pk_fma_f32 v[172:173], v[100:101], v[2:3], v[172:173]
	v_pk_fma_f32 v[172:173], v[102:103], v[4:5], v[172:173]
	v_pk_fma_f32 v[172:173], v[104:105], v[6:7], v[172:173]
	v_pk_fma_f32 v[172:173], v[106:107], v[8:9], v[172:173]
	v_pk_fma_f32 v[172:173], v[108:109], v[10:11], v[172:173]
	v_pk_fma_f32 v[172:173], v[110:111], v[12:13], v[172:173]
	v_pk_fma_f32 v[172:173], v[112:113], v[14:15], v[172:173]
	v_pk_fma_f32 v[172:173], v[114:115], v[16:17], v[172:173]
	ds_read_b128 v[100:103], v186 offset:32960
	ds_read_b128 v[104:107], v186 offset:32976
	ds_read_b128 v[108:111], v186 offset:32992
	ds_read_b128 v[112:115], v186 offset:33008
	s_waitcnt lgkmcnt(8)
	v_pk_fma_f32 v[172:173], v[68:69], v[18:19], v[172:173]
	v_pk_fma_f32 v[172:173], v[70:71], v[20:21], v[172:173]
	v_pk_fma_f32 v[172:173], v[72:73], v[22:23], v[172:173]
	v_pk_fma_f32 v[172:173], v[74:75], v[24:25], v[172:173]
	v_pk_fma_f32 v[172:173], v[76:77], v[26:27], v[172:173]
	v_pk_fma_f32 v[172:173], v[78:79], v[28:29], v[172:173]
	v_pk_fma_f32 v[172:173], v[80:81], v[30:31], v[172:173]
	v_pk_fma_f32 v[172:173], v[82:83], v[32:33], v[172:173]
	s_waitcnt lgkmcnt(4)
	v_pk_fma_f32 v[172:173], v[84:85], v[34:35], v[172:173]
	v_pk_fma_f32 v[172:173], v[86:87], v[36:37], v[172:173]
	v_pk_fma_f32 v[172:173], v[88:89], v[38:39], v[172:173]
	v_pk_fma_f32 v[172:173], v[90:91], v[40:41], v[172:173]
	v_pk_fma_f32 v[172:173], v[92:93], v[42:43], v[172:173]
	v_pk_fma_f32 v[172:173], v[94:95], v[44:45], v[172:173]
	v_pk_fma_f32 v[172:173], v[96:97], v[46:47], v[172:173]
	v_pk_fma_f32 v[172:173], v[98:99], v[48:49], v[172:173]
	s_waitcnt lgkmcnt(0)
	v_pk_fma_f32 v[172:173], v[100:101], v[50:51], v[172:173]
	v_pk_fma_f32 v[172:173], v[102:103], v[52:53], v[172:173]
	v_pk_fma_f32 v[172:173], v[104:105], v[54:55], v[172:173]
	v_pk_fma_f32 v[172:173], v[106:107], v[56:57], v[172:173]
	v_pk_fma_f32 v[172:173], v[108:109], v[58:59], v[172:173]
	v_pk_fma_f32 v[172:173], v[110:111], v[60:61], v[172:173]
	v_pk_fma_f32 v[172:173], v[112:113], v[62:63], v[172:173]
	v_pk_fma_f32 v[172:173], v[114:115], v[64:65], v[172:173]
	v_add_f32_e32 v146, v156, v157
	v_add_f32_e32 v147, v158, v159
	v_add_f32_e32 v148, v160, v161
	v_add_f32_e32 v149, v162, v163
	v_add_f32_e32 v150, v164, v165
	v_add_f32_e32 v151, v166, v167
	v_add_f32_e32 v152, v168, v169
	v_add_f32_e32 v153, v170, v171
	v_add_f32_e32 v190, v172, v173
	s_or_b64 exec, exec, s[18:19]
	v_add_u32_e32 v2, 0x9000, v187
	ds_write2_b32 v2, v146, v147 offset1:32
	ds_write2_b32 v2, v148, v149 offset0:64 offset1:96
	ds_write2_b32 v2, v150, v151 offset0:128 offset1:160
	ds_write2_b32 v2, v152, v153 offset0:192 offset1:224
	ds_write_b32 v187, v190 offset:37888
	s_waitcnt lgkmcnt(0)
	s_barrier
	s_and_saveexec_b64 s[4:5], s[2:3]
	s_cbranch_execz .LBB0_7
	s_load_dwordx16 s[44:59], s[0:1], 0x0
	s_mul_i32 s19, s41, 0x6000
	s_mul_hi_i32 s18, s41, 0x6000
	v_mov_b32_e32 v143, v133
	s_waitcnt lgkmcnt(0)
	s_add_u32 s19, s54, s19
	s_addc_u32 s42, s55, s18
	s_add_u32 s18, s19, s16
	s_addc_u32 s19, s42, s17
	global_load_dword v6, v142, s[18:19]
	v_mad_i64_i32 v[2:3], s[18:19], s41, 9, v[136:137]
	v_readlane_b32 s18, v249, 27
	v_readlane_b32 s19, v249, 28
	ds_read_b32 v7, v188 offset:36864
	ds_read_b32 v8, v188 offset:38016
	ds_read_b32 v9, v188 offset:39168
	ds_read_b32 v10, v188 offset:40320
	ds_read_b32 v11, v188 offset:41472
	ds_read_b32 v12, v188 offset:42624
	ds_read_b32 v13, v188 offset:43776
	ds_read_b32 v14, v188 offset:44928
	ds_read_b32 v15, v188 offset:46080
	ds_read_b32 v16, v188 offset:47232
	ds_read_b32 v17, v188 offset:48384
	ds_read_b32 v18, v188 offset:49536
	ds_read_b32 v19, v188 offset:50688
	ds_read_b32 v20, v188 offset:51840
	ds_read_b32 v21, v188 offset:52992
	ds_read_b32 v22, v188 offset:54144
	v_mov_b64_e32 v[4:5], s[18:19]
	v_mad_u64_u32 v[4:5], s[18:19], v2, s21, v[4:5]
	v_mad_i32_i24 v5, v3, s21, v5
	v_lshl_add_u64 v[2:3], v[4:5], 0, s[16:17]
	s_waitcnt lgkmcnt(14)
	v_add_f32_e32 v4, 0, v7
	v_add_f32_e32 v4, v4, v8
	s_waitcnt lgkmcnt(13)
	v_add_f32_e32 v4, v4, v9
	s_waitcnt lgkmcnt(12)
	v_add_f32_e32 v4, v4, v10
	s_waitcnt lgkmcnt(11)
	v_add_f32_e32 v4, v4, v11
	s_waitcnt lgkmcnt(10)
	v_add_f32_e32 v4, v4, v12
	s_waitcnt lgkmcnt(9)
	v_add_f32_e32 v4, v4, v13
	s_waitcnt lgkmcnt(8)
	v_add_f32_e32 v4, v4, v14
	s_waitcnt lgkmcnt(7)
	v_add_f32_e32 v4, v4, v15
	s_waitcnt lgkmcnt(6)
	v_add_f32_e32 v4, v4, v16
	s_waitcnt lgkmcnt(5)
	v_add_f32_e32 v4, v4, v17
	s_waitcnt lgkmcnt(4)
	v_add_f32_e32 v4, v4, v18
	s_waitcnt lgkmcnt(3)
	v_add_f32_e32 v4, v4, v19
	s_waitcnt lgkmcnt(2)
	v_add_f32_e32 v4, v4, v20
	s_waitcnt lgkmcnt(1)
	v_add_f32_e32 v4, v4, v21
	s_waitcnt lgkmcnt(0)
	v_add_f32_e32 v4, v4, v22
	v_lshl_add_u64 v[2:3], v[2:3], 0, v[142:143]
	s_waitcnt vmcnt(0)
	v_add_f32_e32 v4, v4, v6
	global_store_dword v[2:3], v4, off
	s_branch .LBB0_7
